# grid barrier: the per-workgroup L1 invalidate is issued at arrival (before the release spin) instead of after the release is observed
# speedup vs baseline: 1.0306x; 1.0065x over previous
.LBB0_171:
	s_or_b64 exec, exec, s[4:5]
	v_cvt_f32_u32_e32 v4, v2
	s_waitcnt vmcnt(0)
	v_readfirstlane_b32 s0, v3
	v_sub_u32_e32 v3, 0, v2
	v_rcp_iflag_f32_e32 v4, v4
	v_add_u32_e32 v5, s0, v1
	v_mul_f32_e32 v4, 0x4f7ffffe, v4
	v_cvt_u32_f32_e32 v4, v4
	v_mul_lo_u32 v1, v3, v4
	v_mul_hi_u32 v1, v4, v1
	v_add_u32_e32 v1, v4, v1
	v_mul_hi_u32 v1, v5, v1
	v_mul_lo_u32 v3, v1, v2
	v_sub_u32_e32 v3, v5, v3
	v_add_u32_e32 v4, 1, v1
	v_cmp_ge_u32_e32 vcc, v3, v2
	s_nop 1
	v_cndmask_b32_e32 v1, v1, v4, vcc
	v_sub_u32_e32 v4, v3, v2
	v_cndmask_b32_e32 v3, v3, v4, vcc
	v_add_u32_e32 v4, 1, v1
	v_cmp_ge_u32_e32 vcc, v3, v2
	v_add_u32_e32 v3, 1, v5
	s_nop 0
	v_cndmask_b32_e32 v1, v1, v4, vcc
	v_mul_lo_u32 v4, v2, v1
	v_add_u32_e32 v2, v4, v2
	v_cmp_ne_u32_e32 vcc, v3, v2
	s_and_saveexec_b64 s[0:1], vcc
	s_xor_b64 s[4:5], exec, s[0:1]
	s_cbranch_execz .LBB0_185
	buffer_inv sc1
	v_readlane_b32 s0, v253, 45
	v_readlane_b32 s1, v253, 46
	s_waitcnt lgkmcnt(0)
	s_nop 3
	global_load_dword v0, v193, s[0:1] sc1
	s_waitcnt vmcnt(0)
	v_cmp_eq_u32_e32 vcc, v0, v1
	s_and_saveexec_b64 s[10:11], vcc
	s_cbranch_execz .LBB0_184
	s_mov_b32 s0, 1
	s_mov_b64 s[12:13], 0
	s_branch .LBB0_175

.LBB0_184:
	s_or_b64 exec, exec, s[10:11]
	s_waitcnt vmcnt(0)
	s_waitcnt vmcnt(0)

.LBB0_188:
	s_or_b64 exec, exec, s[10:11]
	s_waitcnt vmcnt(0)
	buffer_inv sc1
	v_readfirstlane_b32 s0, v2
	v_cvt_f32_u32_e32 v2, v0
	v_sub_u32_e32 v3, 0, v0
	v_add_u32_e32 v1, s0, v1
	v_readlane_b32 s0, v253, 49
	v_rcp_iflag_f32_e32 v2, v2
	v_readlane_b32 s1, v253, 50
	s_mov_b64 s[10:11], -1
	v_mul_f32_e32 v2, 0x4f7ffffe, v2
	v_cvt_u32_f32_e32 v2, v2
	v_mul_lo_u32 v3, v3, v2
	v_mul_hi_u32 v3, v2, v3
	v_add_u32_e32 v2, v2, v3
	v_mul_hi_u32 v2, v1, v2
	v_mul_lo_u32 v3, v2, v0
	v_sub_u32_e32 v3, v1, v3
	v_cmp_ge_u32_e32 vcc, v3, v0
	v_add_u32_e32 v4, 1, v2
	v_add_u32_e32 v1, 1, v1
	v_cndmask_b32_e32 v2, v2, v4, vcc
	v_sub_u32_e32 v4, v3, v0
	v_cndmask_b32_e32 v3, v3, v4, vcc
	v_cmp_ge_u32_e32 vcc, v3, v0
	v_add_u32_e32 v3, 1, v2
	s_nop 0
	v_cndmask_b32_e32 v2, v2, v3, vcc
	v_mul_lo_u32 v3, v0, v2
	v_add_u32_e32 v0, v3, v0
	v_cmp_ne_u32_e32 vcc, v1, v0
	v_mov_b64_e32 v[0:1], s[0:1]
	s_and_saveexec_b64 s[4:5], vcc
	s_cbranch_execz .LBB0_200
	v_readlane_b32 s0, v253, 49
	v_readlane_b32 s1, v253, 50
	s_mov_b64 s[12:13], 0
	s_nop 3
	global_load_dword v0, v193, s[0:1] sc1
	s_waitcnt vmcnt(0)
	v_cmp_eq_u32_e32 vcc, v0, v2
	s_and_saveexec_b64 s[10:11], vcc
	s_cbranch_execz .LBB0_199
	s_mov_b32 s0, 1
	s_branch .LBB0_192

.LBB0_202:
	s_or_b64 exec, exec, s[4:5]
	s_mov_b64 s[4:5], exec
	v_mbcnt_lo_u32_b32 v0, s4, 0
	v_mbcnt_hi_u32_b32 v0, s5, v0
	v_cmp_eq_u32_e32 vcc, 0, v0
	s_waitcnt vmcnt(0)
	s_and_saveexec_b64 s[10:11], vcc
	s_cbranch_execz .LBB0_204
	s_bcnt1_i32_b64 s0, s[4:5]
	v_mov_b32_e32 v0, s0
	v_readlane_b32 s0, v253, 45
	v_readlane_b32 s1, v253, 46
	s_nop 4
	global_atomic_add v193, v0, s[0:1]

.LBB0_1162:
	s_or_b64 exec, exec, s[4:5]
	s_mov_b64 s[4:5], exec
	v_mbcnt_lo_u32_b32 v0, s4, 0
	v_mbcnt_hi_u32_b32 v0, s5, v0
	v_cmp_eq_u32_e32 vcc, 0, v0
	s_waitcnt vmcnt(0)
	s_and_saveexec_b64 s[10:11], vcc
	s_cbranch_execnz .LBB0_1163
	s_getpc_b64 s[98:99]
